# GU peeled S1 wait relaxed to vmcnt(16): no longer blocks on the previous iteration's prefetch DMAs
# speedup vs baseline: 1.0001x; 1.0001x over previous
; #define PG8_STAGE(bufoff, gbase, voff) do { _Pragma("unroll") for (int _i = 0; _i < 2; ++_i) \
;         __builtin_amdgcn_global_load_lds((const unsigned*)((const char*)(gbase) + (voff)[_i]), (PG8_LAS unsigned*)(lds + (bufoff) + ldsw + _i * 8192), 16, 0, 0); } while (0)
; #define PG8_LDA(dst, b, h) do { _Pragma("unroll") for (int m = 0; m < 4; ++m) _Pragma("unroll") for (int k = 0; k < 2; ++k) dst[m][k] = *(const PG8_LAS bf16x8*)(lds + PG8_SA(b, h) + aoff + m * 2048 + k * 1024); } while (0)
; #define PG8_LDB(dst, b, h) do { _Pragma("unroll") for (int n = 0; n < 2; ++n) _Pragma("unroll") for (int k = 0; k < 2; ++k) dst[n][k] = *(const PG8_LAS bf16x8*)(lds + PG8_SB(b, h) + boff + n * 2048 + k * 1024); } while (0)
; #define PG8_WAIT_V(n) asm volatile("s_waitcnt vmcnt(" #n ")" ::: "memory")
; #define PG8_WAIT_L(n) asm volatile("s_waitcnt lgkmcnt(" #n ")" ::: "memory")
; #define PG8_BAR __builtin_amdgcn_s_barrier()
; #define PG8_SCHED __builtin_amdgcn_sched_barrier(0)
;     __host__ __device__ bool next(int i, Unit& u) const {
;         if (rev) { const int nr = nwg / G; if (i >= nr) return false; i = nr - 1 - i; }
;         const long L = (long)i * G + c; if (L >= nwg) return false;
;         int wgid = (int)L; { const int q = nwg / NXCD, r = nwg % NXCD, xcd = wgid % NXCD, off = wgid / NXCD; wgid = (xcd < r ? xcd * (q + 1) : r * (q + 1) + (xcd - r) * q) + off; }
;         const int nig = WGM * nN, gid = wgid / nig, fm = gid * WGM, gsz = (nM - fm) < WGM ? (nM - fm) : WGM;
;         u.pm = fm + ((wgid % nig) % gsz); u.pn = (wgid % nig) / gsz; return true;
;     }
; template <class Epi, class Sched, bool ALIGN_EPI = false, bool SP2 = true>
; __device__ __forceinline__ void gemm_phase(PG8_LAS unsigned char* lds, const Gemm g, const Sched& S, const Epi& E) {
;     ...
;             PG8_LDB(B0, 0, 0); PG8_LDB(B1, 0, 1); PG8_SCHED; PG8_LDA(At, 0, 0); PG8_STAGE(PG8_SA(1, 1), a1 + hstepA, voffA);
;             PG8_WAIT_V(8); PG8_WAIT_L(0); PG8_BAR; PG8_MMA(0, 0, At, B0); PG8_MMA(0, 1, At, B1); PG8_BAR; PG8_SCHED;
;             PG8_LDA(At, 0, 1); PG8_STAGE(PG8_SB(0, 0), b2, voffB); PG8_STAGE(PG8_SB(0, 1), b2 + hstep, voffB); PG8_STAGE(PG8_SA(0, 0), a2, voffA);
;             PG8_WAIT_V(8); PG8_WAIT_L(0); PG8_BAR; PG8_MMA(1, 0, At, B0); PG8_MMA(1, 1, At, B1); PG8_BAR; PG8_SCHED;
.Lgu_s1_nofirst:
	v_lshl_add_u64 v[148:149], s[46:47], 0, v[136:137]
	s_add_i32 m0, s29, 0xc000
	s_nop 0
	global_load_lds_dwordx4 v[148:149], off
	v_lshl_add_u64 v[148:149], s[46:47], 0, v[138:139]
	s_add_i32 m0, s29, 0xe000
	s_nop 0
	global_load_lds_dwordx4 v[148:149], off
	s_waitcnt vmcnt(16)
	s_waitcnt lgkmcnt(0)
	s_setprio 1
	s_barrier
	v_mfma_f32_16x16x32_bf16 v[120:123], v[152:155], v[184:187], 0
	v_mfma_f32_16x16x32_bf16 v[112:115], v[160:163], v[184:187], 0
	v_mfma_f32_16x16x32_bf16 v[108:111], v[152:155], v[200:203], 0
	v_mfma_f32_16x16x32_bf16 v[96:99], v[160:163], v[200:203], 0
	v_mfma_f32_16x16x32_bf16 v[92:95], v[152:155], v[208:211], 0
	v_mfma_f32_16x16x32_bf16 v[80:83], v[160:163], v[208:211], 0
	v_mfma_f32_16x16x32_bf16 v[76:79], v[152:155], v[216:219], 0
	v_mfma_f32_16x16x32_bf16 v[64:67], v[160:163], v[216:219], 0
	v_mfma_f32_16x16x32_bf16 v[120:123], v[156:159], v[188:191], v[120:123]
	v_mfma_f32_16x16x32_bf16 v[112:115], v[164:167], v[188:191], v[112:115]
	v_mfma_f32_16x16x32_bf16 v[108:111], v[156:159], v[204:207], v[108:111]
	v_mfma_f32_16x16x32_bf16 v[96:99], v[164:167], v[204:207], v[96:99]
	v_mfma_f32_16x16x32_bf16 v[92:95], v[156:159], v[212:215], v[92:95]
	v_mfma_f32_16x16x32_bf16 v[80:83], v[164:167], v[212:215], v[80:83]
	v_mfma_f32_16x16x32_bf16 v[76:79], v[156:159], v[220:223], v[76:79]
	v_mfma_f32_16x16x32_bf16 v[64:67], v[164:167], v[220:223], v[64:67]
	v_mfma_f32_16x16x32_bf16 v[124:127], v[168:171], v[184:187], 0
	v_mfma_f32_16x16x32_bf16 v[116:119], v[176:179], v[184:187], 0
	v_mfma_f32_16x16x32_bf16 v[104:107], v[168:171], v[200:203], 0
	v_mfma_f32_16x16x32_bf16 v[100:103], v[176:179], v[200:203], 0
	v_mfma_f32_16x16x32_bf16 v[88:91], v[168:171], v[208:211], 0
	v_mfma_f32_16x16x32_bf16 v[84:87], v[176:179], v[208:211], 0
	v_mfma_f32_16x16x32_bf16 v[72:75], v[168:171], v[216:219], 0
	v_mfma_f32_16x16x32_bf16 v[68:71], v[176:179], v[216:219], 0
	v_mfma_f32_16x16x32_bf16 v[124:127], v[172:175], v[188:191], v[124:127]
	v_mfma_f32_16x16x32_bf16 v[116:119], v[180:183], v[188:191], v[116:119]
	v_mfma_f32_16x16x32_bf16 v[104:107], v[172:175], v[204:207], v[104:107]
	v_mfma_f32_16x16x32_bf16 v[100:103], v[180:183], v[204:207], v[100:103]
	v_mfma_f32_16x16x32_bf16 v[88:91], v[172:175], v[212:215], v[88:91]
	v_mfma_f32_16x16x32_bf16 v[84:87], v[180:183], v[212:215], v[84:87]
	v_mfma_f32_16x16x32_bf16 v[72:75], v[172:175], v[220:223], v[72:75]
	v_mfma_f32_16x16x32_bf16 v[68:71], v[180:183], v[220:223], v[68:71]
	s_setprio 0
	s_barrier
	s_add_i32 s14, s70, s28
	v_lshl_add_u64 v[148:149], s[48:49], 0, v[132:133]
	s_mov_b32 m0, s14
	ds_read_b128 v[184:187], v150 offset:16384
	ds_read_b128 v[188:191], v150 offset:17408
	ds_read_b128 v[200:203], v150 offset:18432
	ds_read_b128 v[204:207], v150 offset:19456
	ds_read_b128 v[208:211], v150 offset:20480
	ds_read_b128 v[212:215], v150 offset:21504
	ds_read_b128 v[216:219], v150 offset:22528
	ds_read_b128 v[220:223], v150 offset:23552
	global_load_lds_dwordx4 v[148:149], off
	s_add_i32 m0, s14, 0x2000
	v_lshl_add_u64 v[224:225], s[48:49], 0, v[128:129]
	global_load_lds_dwordx4 v[224:225], off
	v_lshl_add_u64 v[234:235], s[50:51], 0, v[130:131]
	v_lshl_add_u64 v[226:227], s[50:51], 0, v[134:135]
	s_mov_b32 m0, s29
	s_nop 0
	global_load_lds_dwordx4 v[226:227], off
	s_mov_b32 m0, s30
	s_nop 0
	global_load_lds_dwordx4 v[234:235], off
	s_mul_i32 s100, s57, s3
	s_mul_hi_u32 s101, s57, s90
	s_add_i32 s101, s101, s100
	s_mul_i32 s100, s57, s90
	s_add_u32 s40, s100, s2
	s_addc_u32 s41, s101, s33
	v_mov_b64_e32 v[0:1], 0xb00
	v_cmp_lt_i64_e64 s[36:37], s[40:41], v[0:1]
	v_mov_b64_e32 v[0:1], 0xaff
	v_cmp_gt_i64_e32 vcc, s[40:41], v[0:1]
	s_cbranch_vccnz .Lgu_idx_skip
	s_ashr_i32 s100, s40, 31
	s_lshr_b32 s100, s100, 29
	s_add_i32 s100, s40, s100
	s_ashr_i32 s101, s100, 3
	s_and_b32 s100, s100, -8
	s_sub_i32 s100, s40, s100
	s_cmp_lt_i32 s100, 0
	s_cselect_b32 s14, s4, 0x160
	s_mul_i32 s100, s100, s14
	s_add_i32 s100, s100, s101
	s_mul_hi_i32 s101, s100, 0x2e8ba2e9
	s_lshr_b32 s14, s101, 31
	s_ashr_i32 s101, s101, 5
	s_add_i32 s101, s101, s14
	s_lshl_b32 s14, s101, 3
	s_sub_i32 s15, 0x80, s14
	s_min_i32 s15, s15, 8
	s_abs_i32 s17, s15
	v_cvt_f32_u32_e32 v0, s17
	s_sub_i32 s25, 0, s17
	s_mulk_i32 s101, 0xb0
	s_sub_i32 s100, s100, s101
	v_rcp_iflag_f32_e32 v0, v0
	s_abs_i32 s101, s100
	s_xor_b32 s24, s100, s15
	s_ashr_i32 s24, s24, 31
	v_mul_f32_e32 v0, 0x4f7ffffe, v0
	v_cvt_u32_f32_e32 v0, v0
	s_nop 0
	v_readfirstlane_b32 s38, v0
	s_mul_i32 s25, s25, s38
	s_mul_hi_u32 s25, s38, s25
	s_add_i32 s38, s38, s25
	s_mul_hi_u32 s25, s101, s38
	s_mul_i32 s38, s25, s17
	s_sub_i32 s101, s101, s38
	s_add_i32 s39, s25, 1
	s_sub_i32 s38, s101, s17
	s_cmp_ge_u32 s101, s17
	s_cselect_b32 s25, s39, s25
	s_cselect_b32 s101, s38, s101
	s_add_i32 s38, s25, 1
	s_cmp_ge_u32 s101, s17
	s_cselect_b32 s101, s38, s25
	s_xor_b32 s101, s101, s24
	s_sub_i32 s24, s101, s24
	s_mul_i32 s101, s24, s15
	s_sub_i32 s100, s100, s101
	s_add_i32 s38, s14, s100
